# entry code prefetch by one workgroup per XCD, seam prefetch by one in eight
# speedup vs baseline: 1.0003x; 1.0003x over previous
_Z12trunk_kernel2KP:
	s_and_b32 s18, s2, 0xf8
	s_cmp_lg_u32 s18, 0
	s_cbranch_scc1 .Lent_nopf
	s_getpc_b64 s[18:19]
	v_and_b32_e32 v254, 0x3ff, v0
	v_lshlrev_b32_e32 v254, 6, v254
	global_load_dword v255, v254, s[18:19]
